# attention: first key/value tile loads of each query block issued at the top of the block beside the Q loads
# baseline (speedup 1.0000x reference)
.LBB0_440:
	v_mov_b32_e32 v36, v136
	s_lshl_b32 s0, s82, 8
	v_ashrrev_i32_e32 v2, 6, v36
	v_and_b32_e32 v37, 63, v36
	v_readfirstlane_b32 s85, v2
	v_add_u32_e32 v2, s77, v2
	v_ashrrev_i32_e32 v3, 31, v2
	v_and_b32_e32 v35, 31, v36
	v_lshlrev_b64 v[2:3], 12, v[2:3]
	s_lshl_b32 s83, s85, 5
	v_lshl_add_u64 v[2:3], s[20:21], 0, v[2:3]
	v_lshlrev_b32_e32 v132, 2, v37
	v_or_b32_e32 v134, s83, v35
	s_add_u32 s48, s12, s0
	v_lshl_add_u64 v[2:3], v[2:3], 0, v[132:133]
	s_addc_u32 s49, s13, 0
	v_ashrrev_i32_e32 v135, 31, v134
	global_load_dword v4, v[2:3], off
	global_load_dword v5, v[2:3], off offset:2048
	v_lshl_add_u64 v[2:3], s[48:49], 0, v[134:135]
	v_bfe_u32 v34, v36, 5, 1
	v_lshlrev_b64 v[2:3], 10, v[2:3]
	v_lshl_add_u64 v[2:3], s[44:45], 0, v[2:3]
	v_lshlrev_b32_e32 v132, 4, v34
	v_lshl_add_u64 v[2:3], v[2:3], 0, v[132:133]
	global_load_dwordx4 v[80:83], v[2:3], off
	global_load_dwordx4 v[84:87], v[2:3], off offset:32
	global_load_dwordx4 v[88:91], v[2:3], off offset:64
	global_load_dwordx4 v[92:95], v[2:3], off offset:96
	v_ashrrev_i32_e32 v170, 3, v36
	v_and_b32_e32 v171, 7, v36
	v_lshlrev_b32_e32 v172, 3, v171
	v_add_lshl_u32 v173, v170, s12, 9
	v_or3_b32 v172, v173, v172, s78
	s_lshl_b32 s98, s85, 4
	v_lshlrev_b32_e32 v172, 1, v172
	v_or_b32_e32 v173, s12, v37
	s_add_i32 s98, s98, s79
	v_lshl_add_u32 v173, v173, 10, s98
	s_lshl_b32 s99, s82, 18
	v_add_u32_e32 v174, s99, v173
	v_add_u32_e32 v175, s99, v172
	global_load_dwordx4 v[162:165], v175, s[4:5]
	global_load_dwordx4 v[166:169], v174, s[8:9]
	v_lshl_add_u32 v2, v36, 2, 0
	s_cmp_lt_u32 s82, 4
	s_mov_b64 s[0:1], -1
	s_waitcnt vmcnt(6)
	v_add_f32_e32 v3, v4, v5
	ds_write_b32 v2, v3 offset:36864
	s_waitcnt lgkmcnt(0)
	s_barrier
	s_cbranch_scc1 .LBB0_451
	v_cmp_lt_i32_e32 vcc, v138, v139
	v_and_b32_e32 v40, 32, v36
	v_mov_b32_e32 v39, 0
	v_cndmask_b32_e32 v2, v137, v138, vcc
	v_lshlrev_b32_e32 v38, 2, v2
	s_waitcnt vmcnt(4)
	v_lshlrev_b32_e32 v3, 16, v84
	v_lshlrev_b32_e32 v2, 16, v80
	v_and_b32_e32 v5, 0xffff0000, v84
	v_and_b32_e32 v4, 0xffff0000, v80
	v_lshlrev_b32_e32 v7, 16, v85
	v_lshlrev_b32_e32 v6, 16, v81
	v_and_b32_e32 v9, 0xffff0000, v85
	v_and_b32_e32 v8, 0xffff0000, v81
	v_lshlrev_b32_e32 v11, 16, v86
	v_lshlrev_b32_e32 v10, 16, v82
	v_and_b32_e32 v13, 0xffff0000, v86
	v_and_b32_e32 v12, 0xffff0000, v82
	v_lshlrev_b32_e32 v15, 16, v87
	v_lshlrev_b32_e32 v14, 16, v83
	v_and_b32_e32 v17, 0xffff0000, v87
	v_and_b32_e32 v16, 0xffff0000, v83
	s_waitcnt vmcnt(2)
	v_lshlrev_b32_e32 v19, 16, v92
	v_lshlrev_b32_e32 v18, 16, v88
	v_and_b32_e32 v21, 0xffff0000, v92
	v_and_b32_e32 v20, 0xffff0000, v88
	v_lshlrev_b32_e32 v23, 16, v93
	v_lshlrev_b32_e32 v22, 16, v89
	v_and_b32_e32 v25, 0xffff0000, v93
	v_and_b32_e32 v24, 0xffff0000, v89
	v_lshlrev_b32_e32 v27, 16, v94
	v_lshlrev_b32_e32 v26, 16, v90
	v_and_b32_e32 v29, 0xffff0000, v94
	v_and_b32_e32 v28, 0xffff0000, v90
	v_lshlrev_b32_e32 v31, 16, v95
	v_lshlrev_b32_e32 v30, 16, v91
	v_and_b32_e32 v33, 0xffff0000, v95
	v_and_b32_e32 v32, 0xffff0000, v91
	v_add_u32_e32 v40, s30, v40
	v_mov_b32_e32 v41, 0xff800000
	s_mov_b32 s6, 0
	v_mov_b32_e32 v42, 0xff800000
	v_mov_b32_e32 v45, 0xff800000
	v_mov_b32_e32 v43, 0
	v_mov_b32_e32 v44, 0

.LBB0_453:
	v_ashrrev_i32_e32 v10, 3, v36
	v_and_b32_e32 v11, 7, v36
	v_lshlrev_b32_e32 v2, 3, v11
	v_add_lshl_u32 v3, v10, s12, 9
	v_or3_b32 v2, v3, v2, s78
	s_lshl_b32 s0, s85, 4
	v_lshlrev_b32_e32 v141, 1, v2
	v_or_b32_e32 v2, s12, v37
	s_add_i32 s0, s0, s79
	v_lshl_add_u32 v142, v2, 10, s0
	s_lshl_b32 s0, s82, 18
	v_add_u32_e32 v6, s0, v142
	v_add_u32_e32 v2, s0, v141
	s_mul_i32 s84, s85, 0x480
	v_lshlrev_b32_e32 v12, 1, v36
	v_lshrrev_b32_e32 v13, 1, v36
	v_and_b32_e32 v143, 51, v36
	v_mul_lo_u32 v144, v10, s31
	v_lshlrev_b32_e32 v145, 4, v11
	v_and_b32_e32 v10, 8, v12
	v_and_b32_e32 v11, 4, v13
	s_add_i32 s1, s84, 0
	s_bitset1_b32 s0, 16
	v_lshl_add_u32 v13, v143, 1, s1
	v_lshlrev_b32_e32 v146, 1, v10
	v_lshlrev_b32_e32 v147, 1, v11
	v_add3_u32 v12, 0, v144, v145
	v_add3_u32 v10, v13, v146, v147
	v_add_u32_e32 v13, s0, v141
	v_add_u32_e32 v11, s0, v142
	s_mov_b64 s[0:1], -1
	s_cmp_gt_i32 s85, -1
	v_or_b32_e32 v148, 32, v132
	v_or_b32_e32 v149, 64, v132
	v_or_b32_e32 v150, 0x60, v132
	s_waitcnt vmcnt(1)
	ds_write_b128 v12, v[162:165]
	s_waitcnt vmcnt(0)
	ds_write_b16 v10, v166 offset:18432
	ds_write_b16_d16_hi v10, v166 offset:18576
	ds_write_b16 v10, v167 offset:18720
	ds_write_b16_d16_hi v10, v167 offset:18864
	ds_write_b16 v10, v168 offset:19008
	ds_write_b16_d16_hi v10, v168 offset:19152
	ds_write_b16 v10, v169 offset:19296
	ds_write_b16_d16_hi v10, v169 offset:19440
	s_waitcnt lgkmcnt(0)
	s_barrier
	global_load_dwordx4 v[96:99], v13, s[4:5]
	global_load_dwordx4 v[100:103], v11, s[8:9]
	s_cbranch_scc1 .LBB0_455
	v_or_b32_e32 v36, 32, v132
	v_or_b32_e32 v37, 64, v132
	v_or_b32_e32 v38, 0x60, v132
	s_mov_b64 s[0:1], 0
